# flagged relaxed wait with per-epilogue store count (vmcnt(24) where the epilogue has 16 stores)
# baseline (speedup 1.0000x reference)
.LBB0_449:
	s_lshl_b32 s73, s59, 19
	s_and_b64 s[6:7], s[6:7], exec
	v_mov_b32_e32 v2, 0
	s_cselect_b32 s6, s73, s17
	s_add_i32 s7, s17, 0x60080
	s_addk_i32 s16, 0x100
	s_mov_b32 s17, -2
	ds_read_b128 v[118:121], v197
	ds_read_b128 v[126:129], v197 offset:1024
	ds_read_b128 v[130:133], v197 offset:2048
	ds_read_b128 v[138:141], v197 offset:3072
	s_add_i32 s10, s7, 0xfffa0080
	s_cmp_eq_u32 s17, 12
	s_cselect_b32 s87, s6, s10
	s_cselect_b32 s86, s72, s16
	s_or_b32 s88, s87, 0x80
	s_add_i32 s10, s7, 0xfffe0000
	s_mov_b32 m0, s41
	ds_read_b128 v[146:149], v198
	ds_read_b128 v[150:153], v198 offset:1024
	ds_read_b128 v[154:157], v198 offset:2048
	ds_read_b128 v[158:161], v198 offset:3072
	ds_read_b128 v[162:165], v198 offset:4096
	ds_read_b128 v[166:169], v198 offset:5120
	ds_read_b128 v[170:173], v198 offset:6144
	ds_read_b128 v[174:177], v198 offset:7168
	buffer_load_dwordx4 v1, s[48:51], s10 offen lds
	s_mov_b32 m0, s42
	s_nop 0
	buffer_load_dwordx4 v1, s[48:51], s7 offen lds
	s_waitcnt lgkmcnt(8)
	s_barrier
	s_waitcnt lgkmcnt(0)
	s_setprio 1
	s_waitcnt lgkmcnt(7)
	v_mfma_f32_16x16x32_bf16 v[142:145], v[118:121], v[146:149], 0
	v_mfma_f32_16x16x32_bf16 v[134:137], v[130:133], v[146:149], 0
	s_waitcnt lgkmcnt(5)
	v_mfma_f32_16x16x32_bf16 v[122:125], v[118:121], v[154:157], 0
	v_mfma_f32_16x16x32_bf16 v[114:117], v[130:133], v[154:157], 0
	s_waitcnt lgkmcnt(3)
	v_mfma_f32_16x16x32_bf16 v[94:97], v[118:121], v[162:165], 0
	v_mfma_f32_16x16x32_bf16 v[90:93], v[130:133], v[162:165], 0
	s_waitcnt lgkmcnt(1)
	v_mfma_f32_16x16x32_bf16 v[82:85], v[118:121], v[170:173], 0
	v_mfma_f32_16x16x32_bf16 v[74:77], v[130:133], v[170:173], 0
	v_mfma_f32_16x16x32_bf16 v[142:145], v[126:129], v[150:153], v[142:145]
	v_mfma_f32_16x16x32_bf16 v[134:137], v[138:141], v[150:153], v[134:137]
	v_mfma_f32_16x16x32_bf16 v[122:125], v[126:129], v[158:161], v[122:125]
	v_mfma_f32_16x16x32_bf16 v[114:117], v[138:141], v[158:161], v[114:117]
	v_mfma_f32_16x16x32_bf16 v[94:97], v[126:129], v[166:169], v[94:97]
	v_mfma_f32_16x16x32_bf16 v[90:93], v[138:141], v[166:169], v[90:93]
	s_waitcnt lgkmcnt(0)
	v_mfma_f32_16x16x32_bf16 v[82:85], v[126:129], v[174:177], v[82:85]
	v_mfma_f32_16x16x32_bf16 v[74:77], v[138:141], v[174:177], v[74:77]
	s_setprio 0
	s_barrier
	s_mov_b32 m0, s21
	s_mov_b32 s10, s50
	s_mov_b32 s11, s51
	ds_read_b128 v[178:181], v199
	ds_read_b128 v[182:185], v199 offset:1024
	ds_read_b128 v[190:193], v199 offset:2048
	ds_read_b128 v[202:205], v199 offset:3072
	buffer_load_dwordx4 v194, s[8:11], s86 offen lds
	s_add_i32 s33, s86, 0x20000
	s_mov_b32 m0, s22
	s_nop 0
	buffer_load_dwordx4 v194, s[8:11], s33 offen lds
	s_barrier
	s_waitcnt lgkmcnt(0)
	s_setprio 1
	s_waitcnt lgkmcnt(3)
	v_mfma_f32_16x16x32_bf16 v[110:113], v[178:181], v[146:149], 0
	s_waitcnt lgkmcnt(1)
	v_mfma_f32_16x16x32_bf16 v[106:109], v[190:193], v[146:149], 0
	v_mfma_f32_16x16x32_bf16 v[102:105], v[178:181], v[154:157], 0
	v_mfma_f32_16x16x32_bf16 v[98:101], v[190:193], v[154:157], 0
	v_mfma_f32_16x16x32_bf16 v[86:89], v[178:181], v[162:165], 0
	v_mfma_f32_16x16x32_bf16 v[78:81], v[190:193], v[162:165], 0
	v_mfma_f32_16x16x32_bf16 v[70:73], v[178:181], v[170:173], 0
	v_mfma_f32_16x16x32_bf16 v[66:69], v[190:193], v[170:173], 0
	v_mfma_f32_16x16x32_bf16 v[110:113], v[182:185], v[150:153], v[110:113]
	s_waitcnt lgkmcnt(0)
	v_mfma_f32_16x16x32_bf16 v[106:109], v[202:205], v[150:153], v[106:109]
	v_mfma_f32_16x16x32_bf16 v[102:105], v[182:185], v[158:161], v[102:105]
	v_mfma_f32_16x16x32_bf16 v[98:101], v[202:205], v[158:161], v[98:101]
	v_mfma_f32_16x16x32_bf16 v[86:89], v[182:185], v[166:169], v[86:89]
	v_mfma_f32_16x16x32_bf16 v[78:81], v[202:205], v[166:169], v[78:81]
	v_mfma_f32_16x16x32_bf16 v[70:73], v[182:185], v[174:177], v[70:73]
	v_mfma_f32_16x16x32_bf16 v[66:69], v[202:205], v[174:177], v[66:69]
	s_setprio 0
	s_mov_b32 m0, s20
	s_barrier
	ds_read_b128 v[146:149], v198 offset:16384
	ds_read_b128 v[150:153], v198 offset:17408
	ds_read_b128 v[154:157], v198 offset:18432
	ds_read_b128 v[158:161], v198 offset:19456
	ds_read_b128 v[162:165], v198 offset:20480
	ds_read_b128 v[166:169], v198 offset:21504
	ds_read_b128 v[170:173], v198 offset:22528
	ds_read_b128 v[174:177], v198 offset:23552
	buffer_load_dwordx4 v1, s[48:51], s87 offen lds
	s_add_i32 s33, s87, 0x20000
	s_mov_b32 m0, s23
	s_nop 0
	buffer_load_dwordx4 v1, s[48:51], s33 offen lds
	s_barrier
	s_waitcnt lgkmcnt(0)
	s_setprio 1
	s_waitcnt lgkmcnt(7)
	v_mfma_f32_16x16x32_bf16 v[62:65], v[118:121], v[146:149], 0
	v_mfma_f32_16x16x32_bf16 v[58:61], v[130:133], v[146:149], 0
	s_waitcnt lgkmcnt(5)
	v_mfma_f32_16x16x32_bf16 v[50:53], v[118:121], v[154:157], 0
	v_mfma_f32_16x16x32_bf16 v[42:45], v[130:133], v[154:157], 0
	s_waitcnt lgkmcnt(3)
	v_mfma_f32_16x16x32_bf16 v[34:37], v[118:121], v[162:165], 0
	v_mfma_f32_16x16x32_bf16 v[26:29], v[130:133], v[162:165], 0
	s_waitcnt lgkmcnt(1)
	v_mfma_f32_16x16x32_bf16 v[18:21], v[118:121], v[170:173], 0
	v_mfma_f32_16x16x32_bf16 v[10:13], v[130:133], v[170:173], 0
	v_mfma_f32_16x16x32_bf16 v[62:65], v[126:129], v[150:153], v[62:65]
	v_mfma_f32_16x16x32_bf16 v[58:61], v[138:141], v[150:153], v[58:61]
	v_mfma_f32_16x16x32_bf16 v[50:53], v[126:129], v[158:161], v[50:53]
	v_mfma_f32_16x16x32_bf16 v[42:45], v[138:141], v[158:161], v[42:45]
	v_mfma_f32_16x16x32_bf16 v[34:37], v[126:129], v[166:169], v[34:37]
	v_mfma_f32_16x16x32_bf16 v[26:29], v[138:141], v[166:169], v[26:29]
	s_waitcnt lgkmcnt(0)
	v_mfma_f32_16x16x32_bf16 v[18:21], v[126:129], v[174:177], v[18:21]
	v_mfma_f32_16x16x32_bf16 v[10:13], v[138:141], v[174:177], v[10:13]
	s_setprio 0
	s_barrier
	s_mov_b32 m0, s24
	s_add_i32 s33, s86, 0x40000
	buffer_load_dwordx4 v194, s[8:11], s33 offen lds
	s_add_i32 s33, s86, 0x60000
	s_mov_b32 m0, s25
	s_nop 0
	buffer_load_dwordx4 v194, s[8:11], s33 offen lds
	s_cmp_eq_u32 s100, 0
	s_cbranch_scc1 .Lfw_2_a_p
	s_waitcnt vmcnt(24)
	s_mov_b32 s100, 0
	s_branch .Lfw_2_b_p

.LBB0_1019:
	s_lshl_b32 s38, s36, 19
	s_and_b64 s[6:7], s[6:7], exec
	v_mov_b32_e32 v2, 0
	s_cselect_b32 s6, s38, s47
	s_add_i32 s7, s47, 0x60080
	s_addk_i32 s46, 0x100
	s_mov_b32 s47, -2
	ds_read_b128 v[134:137], v141
	ds_read_b128 v[146:149], v141 offset:1024
	ds_read_b128 v[150:153], v141 offset:2048
	ds_read_b128 v[154:157], v141 offset:3072
	s_add_i32 s10, s7, 0xfffa0080
	s_cmp_eq_u32 s47, 12
	s_cselect_b32 s50, s6, s10
	s_cselect_b32 s49, s37, s46
	s_or_b32 s51, s50, 0x80
	s_add_i32 s10, s7, 0xfffe0000
	s_mov_b32 m0, s29
	ds_read_b128 v[158:161], v142
	ds_read_b128 v[162:165], v142 offset:1024
	ds_read_b128 v[166:169], v142 offset:2048
	ds_read_b128 v[170:173], v142 offset:3072
	ds_read_b128 v[174:177], v142 offset:4096
	ds_read_b128 v[178:181], v142 offset:5120
	ds_read_b128 v[182:185], v142 offset:6144
	ds_read_b128 v[186:189], v142 offset:7168
	buffer_load_dwordx4 v1, s[40:43], s10 offen lds
	s_mov_b32 m0, s30
	s_nop 0
	buffer_load_dwordx4 v1, s[40:43], s7 offen lds
	s_waitcnt lgkmcnt(8)
	s_barrier
	s_waitcnt lgkmcnt(0)
	s_setprio 1
	s_waitcnt lgkmcnt(7)
	v_mfma_f32_16x16x32_bf16 v[126:129], v[134:137], v[158:161], 0
	v_mfma_f32_16x16x32_bf16 v[122:125], v[150:153], v[158:161], 0
	s_waitcnt lgkmcnt(5)
	v_mfma_f32_16x16x32_bf16 v[118:121], v[134:137], v[166:169], 0
	v_mfma_f32_16x16x32_bf16 v[110:113], v[150:153], v[166:169], 0
	s_waitcnt lgkmcnt(3)
	v_mfma_f32_16x16x32_bf16 v[102:105], v[134:137], v[174:177], 0
	v_mfma_f32_16x16x32_bf16 v[94:97], v[150:153], v[174:177], 0
	s_waitcnt lgkmcnt(1)
	v_mfma_f32_16x16x32_bf16 v[86:89], v[134:137], v[182:185], 0
	v_mfma_f32_16x16x32_bf16 v[78:81], v[150:153], v[182:185], 0
	v_mfma_f32_16x16x32_bf16 v[126:129], v[146:149], v[162:165], v[126:129]
	v_mfma_f32_16x16x32_bf16 v[122:125], v[154:157], v[162:165], v[122:125]
	v_mfma_f32_16x16x32_bf16 v[118:121], v[146:149], v[170:173], v[118:121]
	v_mfma_f32_16x16x32_bf16 v[110:113], v[154:157], v[170:173], v[110:113]
	v_mfma_f32_16x16x32_bf16 v[102:105], v[146:149], v[178:181], v[102:105]
	v_mfma_f32_16x16x32_bf16 v[94:97], v[154:157], v[178:181], v[94:97]
	s_waitcnt lgkmcnt(0)
	v_mfma_f32_16x16x32_bf16 v[86:89], v[146:149], v[186:189], v[86:89]
	v_mfma_f32_16x16x32_bf16 v[78:81], v[154:157], v[186:189], v[78:81]
	s_setprio 0
	s_barrier
	s_mov_b32 m0, s15
	s_mov_b32 s10, s42
	s_mov_b32 s11, s43
	ds_read_b128 v[190:193], v143
	ds_read_b128 v[194:197], v143 offset:1024
	ds_read_b128 v[198:201], v143 offset:2048
	ds_read_b128 v[202:205], v143 offset:3072
	buffer_load_dwordx4 v138, s[8:11], s49 offen lds
	s_add_i32 s33, s49, 0x20000
	s_mov_b32 m0, s16
	s_nop 0
	buffer_load_dwordx4 v138, s[8:11], s33 offen lds
	s_barrier
	s_waitcnt lgkmcnt(0)
	s_setprio 1
	s_waitcnt lgkmcnt(3)
	v_mfma_f32_16x16x32_bf16 v[114:117], v[190:193], v[158:161], 0
	s_waitcnt lgkmcnt(1)
	v_mfma_f32_16x16x32_bf16 v[106:109], v[198:201], v[158:161], 0
	v_mfma_f32_16x16x32_bf16 v[98:101], v[190:193], v[166:169], 0
	v_mfma_f32_16x16x32_bf16 v[90:93], v[198:201], v[166:169], 0
	v_mfma_f32_16x16x32_bf16 v[82:85], v[190:193], v[174:177], 0
	v_mfma_f32_16x16x32_bf16 v[74:77], v[198:201], v[174:177], 0
	v_mfma_f32_16x16x32_bf16 v[70:73], v[190:193], v[182:185], 0
	v_mfma_f32_16x16x32_bf16 v[66:69], v[198:201], v[182:185], 0
	v_mfma_f32_16x16x32_bf16 v[114:117], v[194:197], v[162:165], v[114:117]
	s_waitcnt lgkmcnt(0)
	v_mfma_f32_16x16x32_bf16 v[106:109], v[202:205], v[162:165], v[106:109]
	v_mfma_f32_16x16x32_bf16 v[98:101], v[194:197], v[170:173], v[98:101]
	v_mfma_f32_16x16x32_bf16 v[90:93], v[202:205], v[170:173], v[90:93]
	v_mfma_f32_16x16x32_bf16 v[82:85], v[194:197], v[178:181], v[82:85]
	v_mfma_f32_16x16x32_bf16 v[74:77], v[202:205], v[178:181], v[74:77]
	v_mfma_f32_16x16x32_bf16 v[70:73], v[194:197], v[186:189], v[70:73]
	v_mfma_f32_16x16x32_bf16 v[66:69], v[202:205], v[186:189], v[66:69]
	s_setprio 0
	s_mov_b32 m0, s14
	s_barrier
	ds_read_b128 v[158:161], v142 offset:16384
	ds_read_b128 v[162:165], v142 offset:17408
	ds_read_b128 v[166:169], v142 offset:18432
	ds_read_b128 v[170:173], v142 offset:19456
	ds_read_b128 v[174:177], v142 offset:20480
	ds_read_b128 v[178:181], v142 offset:21504
	ds_read_b128 v[182:185], v142 offset:22528
	ds_read_b128 v[186:189], v142 offset:23552
	buffer_load_dwordx4 v1, s[40:43], s50 offen lds
	s_add_i32 s33, s50, 0x20000
	s_mov_b32 m0, s17
	s_nop 0
	buffer_load_dwordx4 v1, s[40:43], s33 offen lds
	s_barrier
	s_waitcnt lgkmcnt(0)
	s_setprio 1
	s_waitcnt lgkmcnt(7)
	v_mfma_f32_16x16x32_bf16 v[62:65], v[134:137], v[158:161], 0
	v_mfma_f32_16x16x32_bf16 v[58:61], v[150:153], v[158:161], 0
	s_waitcnt lgkmcnt(5)
	v_mfma_f32_16x16x32_bf16 v[54:57], v[134:137], v[166:169], 0
	v_mfma_f32_16x16x32_bf16 v[46:49], v[150:153], v[166:169], 0
	s_waitcnt lgkmcnt(3)
	v_mfma_f32_16x16x32_bf16 v[38:41], v[134:137], v[174:177], 0
	v_mfma_f32_16x16x32_bf16 v[30:33], v[150:153], v[174:177], 0
	s_waitcnt lgkmcnt(1)
	v_mfma_f32_16x16x32_bf16 v[22:25], v[134:137], v[182:185], 0
	v_mfma_f32_16x16x32_bf16 v[14:17], v[150:153], v[182:185], 0
	v_mfma_f32_16x16x32_bf16 v[62:65], v[146:149], v[162:165], v[62:65]
	v_mfma_f32_16x16x32_bf16 v[58:61], v[154:157], v[162:165], v[58:61]
	v_mfma_f32_16x16x32_bf16 v[54:57], v[146:149], v[170:173], v[54:57]
	v_mfma_f32_16x16x32_bf16 v[46:49], v[154:157], v[170:173], v[46:49]
	v_mfma_f32_16x16x32_bf16 v[38:41], v[146:149], v[178:181], v[38:41]
	v_mfma_f32_16x16x32_bf16 v[30:33], v[154:157], v[178:181], v[30:33]
	s_waitcnt lgkmcnt(0)
	v_mfma_f32_16x16x32_bf16 v[22:25], v[146:149], v[186:189], v[22:25]
	v_mfma_f32_16x16x32_bf16 v[14:17], v[154:157], v[186:189], v[14:17]
	s_setprio 0
	s_barrier
	s_mov_b32 m0, s18
	s_add_i32 s33, s49, 0x40000
	buffer_load_dwordx4 v138, s[8:11], s33 offen lds
	s_add_i32 s33, s49, 0x60000
	s_mov_b32 m0, s19
	s_nop 0
	buffer_load_dwordx4 v138, s[8:11], s33 offen lds
	s_cmp_eq_u32 s100, 0
	s_cbranch_scc1 .Lfw_5_a_p
	s_waitcnt vmcnt(24)
	s_mov_b32 s100, 0
	s_branch .Lfw_5_b_p

.LBB0_1333:
	s_lshl_b32 s59, s57, 19
	s_and_b64 s[6:7], s[6:7], exec
	v_mov_b32_e32 v2, 0
	s_cselect_b32 s6, s59, s13
	s_add_i32 s7, s13, 0x60080
	s_addk_i32 s12, 0x100
	s_mov_b32 s13, -2
	ds_read_b128 v[130:133], v195
	ds_read_b128 v[134:137], v195 offset:1024
	ds_read_b128 v[138:141], v195 offset:2048
	ds_read_b128 v[142:145], v195 offset:3072
	s_add_i32 s10, s7, 0xfffa0080
	s_cmp_eq_u32 s13, 12
	s_cselect_b32 s79, s6, s10
	s_cselect_b32 s78, s58, s12
	s_or_b32 s84, s79, 0x80
	s_add_i32 s10, s7, 0xfffe0000
	s_mov_b32 m0, s39
	ds_read_b128 v[146:149], v196
	ds_read_b128 v[150:153], v196 offset:1024
	ds_read_b128 v[154:157], v196 offset:2048
	ds_read_b128 v[158:161], v196 offset:3072
	ds_read_b128 v[162:165], v196 offset:4096
	ds_read_b128 v[166:169], v196 offset:5120
	ds_read_b128 v[170:173], v196 offset:6144
	ds_read_b128 v[174:177], v196 offset:7168
	buffer_load_dwordx4 v1, s[48:51], s10 offen lds
	s_mov_b32 m0, s41
	s_nop 0
	buffer_load_dwordx4 v1, s[48:51], s7 offen lds
	s_waitcnt lgkmcnt(8)
	s_barrier
	s_waitcnt lgkmcnt(0)
	s_setprio 1
	s_waitcnt lgkmcnt(7)
	v_mfma_f32_16x16x32_bf16 v[126:129], v[130:133], v[146:149], 0
	v_mfma_f32_16x16x32_bf16 v[122:125], v[138:141], v[146:149], 0
	s_waitcnt lgkmcnt(5)
	v_mfma_f32_16x16x32_bf16 v[110:113], v[130:133], v[154:157], 0
	v_mfma_f32_16x16x32_bf16 v[106:109], v[138:141], v[154:157], 0
	s_waitcnt lgkmcnt(3)
	v_mfma_f32_16x16x32_bf16 v[94:97], v[130:133], v[162:165], 0
	v_mfma_f32_16x16x32_bf16 v[90:93], v[138:141], v[162:165], 0
	s_waitcnt lgkmcnt(1)
	v_mfma_f32_16x16x32_bf16 v[78:81], v[130:133], v[170:173], 0
	v_mfma_f32_16x16x32_bf16 v[74:77], v[138:141], v[170:173], 0
	v_mfma_f32_16x16x32_bf16 v[126:129], v[134:137], v[150:153], v[126:129]
	v_mfma_f32_16x16x32_bf16 v[122:125], v[142:145], v[150:153], v[122:125]
	v_mfma_f32_16x16x32_bf16 v[110:113], v[134:137], v[158:161], v[110:113]
	v_mfma_f32_16x16x32_bf16 v[106:109], v[142:145], v[158:161], v[106:109]
	v_mfma_f32_16x16x32_bf16 v[94:97], v[134:137], v[166:169], v[94:97]
	v_mfma_f32_16x16x32_bf16 v[90:93], v[142:145], v[166:169], v[90:93]
	s_waitcnt lgkmcnt(0)
	v_mfma_f32_16x16x32_bf16 v[78:81], v[134:137], v[174:177], v[78:81]
	v_mfma_f32_16x16x32_bf16 v[74:77], v[142:145], v[174:177], v[74:77]
	s_setprio 0
	s_barrier
	s_mov_b32 m0, s17
	s_mov_b32 s10, s50
	s_mov_b32 s11, s51
	ds_read_b128 v[178:181], v197
	ds_read_b128 v[182:185], v197 offset:1024
	ds_read_b128 v[200:203], v197 offset:2048
	ds_read_b128 v[204:207], v197 offset:3072
	buffer_load_dwordx4 v192, s[8:11], s78 offen lds
	s_add_i32 s33, s78, 0x20000
	s_mov_b32 m0, s18
	s_nop 0
	buffer_load_dwordx4 v192, s[8:11], s33 offen lds
	s_barrier
	s_waitcnt lgkmcnt(0)
	s_setprio 1
	s_waitcnt lgkmcnt(3)
	v_mfma_f32_16x16x32_bf16 v[118:121], v[178:181], v[146:149], 0
	s_waitcnt lgkmcnt(1)
	v_mfma_f32_16x16x32_bf16 v[114:117], v[200:203], v[146:149], 0
	v_mfma_f32_16x16x32_bf16 v[102:105], v[178:181], v[154:157], 0
	v_mfma_f32_16x16x32_bf16 v[98:101], v[200:203], v[154:157], 0
	v_mfma_f32_16x16x32_bf16 v[86:89], v[178:181], v[162:165], 0
	v_mfma_f32_16x16x32_bf16 v[82:85], v[200:203], v[162:165], 0
	v_mfma_f32_16x16x32_bf16 v[70:73], v[178:181], v[170:173], 0
	v_mfma_f32_16x16x32_bf16 v[66:69], v[200:203], v[170:173], 0
	v_mfma_f32_16x16x32_bf16 v[118:121], v[182:185], v[150:153], v[118:121]
	s_waitcnt lgkmcnt(0)
	v_mfma_f32_16x16x32_bf16 v[114:117], v[204:207], v[150:153], v[114:117]
	v_mfma_f32_16x16x32_bf16 v[102:105], v[182:185], v[158:161], v[102:105]
	v_mfma_f32_16x16x32_bf16 v[98:101], v[204:207], v[158:161], v[98:101]
	v_mfma_f32_16x16x32_bf16 v[86:89], v[182:185], v[166:169], v[86:89]
	v_mfma_f32_16x16x32_bf16 v[82:85], v[204:207], v[166:169], v[82:85]
	v_mfma_f32_16x16x32_bf16 v[70:73], v[182:185], v[174:177], v[70:73]
	v_mfma_f32_16x16x32_bf16 v[66:69], v[204:207], v[174:177], v[66:69]
	s_setprio 0
	s_mov_b32 m0, s16
	s_barrier
	ds_read_b128 v[146:149], v196 offset:16384
	ds_read_b128 v[150:153], v196 offset:17408
	ds_read_b128 v[154:157], v196 offset:18432
	ds_read_b128 v[158:161], v196 offset:19456
	ds_read_b128 v[162:165], v196 offset:20480
	ds_read_b128 v[166:169], v196 offset:21504
	ds_read_b128 v[170:173], v196 offset:22528
	ds_read_b128 v[174:177], v196 offset:23552
	buffer_load_dwordx4 v1, s[48:51], s79 offen lds
	s_add_i32 s33, s79, 0x20000
	s_mov_b32 m0, s19
	s_nop 0
	buffer_load_dwordx4 v1, s[48:51], s33 offen lds
	s_barrier
	s_waitcnt lgkmcnt(0)
	s_setprio 1
	s_waitcnt lgkmcnt(7)
	v_mfma_f32_16x16x32_bf16 v[62:65], v[130:133], v[146:149], 0
	v_mfma_f32_16x16x32_bf16 v[58:61], v[138:141], v[146:149], 0
	s_waitcnt lgkmcnt(5)
	v_mfma_f32_16x16x32_bf16 v[46:49], v[130:133], v[154:157], 0
	v_mfma_f32_16x16x32_bf16 v[42:45], v[138:141], v[154:157], 0
	s_waitcnt lgkmcnt(3)
	v_mfma_f32_16x16x32_bf16 v[30:33], v[130:133], v[162:165], 0
	v_mfma_f32_16x16x32_bf16 v[26:29], v[138:141], v[162:165], 0
	s_waitcnt lgkmcnt(1)
	v_mfma_f32_16x16x32_bf16 v[14:17], v[130:133], v[170:173], 0
	v_mfma_f32_16x16x32_bf16 v[10:13], v[138:141], v[170:173], 0
	v_mfma_f32_16x16x32_bf16 v[62:65], v[134:137], v[150:153], v[62:65]
	v_mfma_f32_16x16x32_bf16 v[58:61], v[142:145], v[150:153], v[58:61]
	v_mfma_f32_16x16x32_bf16 v[46:49], v[134:137], v[158:161], v[46:49]
	v_mfma_f32_16x16x32_bf16 v[42:45], v[142:145], v[158:161], v[42:45]
	v_mfma_f32_16x16x32_bf16 v[30:33], v[134:137], v[166:169], v[30:33]
	v_mfma_f32_16x16x32_bf16 v[26:29], v[142:145], v[166:169], v[26:29]
	s_waitcnt lgkmcnt(0)
	v_mfma_f32_16x16x32_bf16 v[14:17], v[134:137], v[174:177], v[14:17]
	v_mfma_f32_16x16x32_bf16 v[10:13], v[142:145], v[174:177], v[10:13]
	s_setprio 0
	s_barrier
	s_mov_b32 m0, s20
	s_add_i32 s33, s78, 0x40000
	buffer_load_dwordx4 v192, s[8:11], s33 offen lds
	s_add_i32 s33, s78, 0x60000
	s_mov_b32 m0, s21
	s_nop 0
	buffer_load_dwordx4 v192, s[8:11], s33 offen lds
	s_cmp_eq_u32 s100, 0
	s_cbranch_scc1 .Lfw_6_a_p
	s_waitcnt vmcnt(24)
	s_mov_b32 s100, 0
	s_branch .Lfw_6_b_p

.LBB0_2150:
	s_lshl_b32 s58, s47, 19
	s_and_b64 s[6:7], s[6:7], exec
	v_mov_b32_e32 v2, 0
	s_cselect_b32 s6, s58, s13
	s_add_i32 s7, s13, 0x60080
	s_addk_i32 s12, 0x100
	s_mov_b32 s13, -2
	ds_read_b128 v[130:133], v195
	ds_read_b128 v[134:137], v195 offset:1024
	ds_read_b128 v[138:141], v195 offset:2048
	ds_read_b128 v[142:145], v195 offset:3072
	s_add_i32 s10, s7, 0xfffa0080
	s_cmp_eq_u32 s13, 12
	s_cselect_b32 s78, s6, s10
	s_cselect_b32 s73, s57, s12
	s_or_b32 s79, s78, 0x80
	s_add_i32 s10, s7, 0xfffe0000
	s_mov_b32 m0, s38
	ds_read_b128 v[146:149], v196
	ds_read_b128 v[150:153], v196 offset:1024
	ds_read_b128 v[154:157], v196 offset:2048
	ds_read_b128 v[158:161], v196 offset:3072
	ds_read_b128 v[162:165], v196 offset:4096
	ds_read_b128 v[166:169], v196 offset:5120
	ds_read_b128 v[170:173], v196 offset:6144
	ds_read_b128 v[174:177], v196 offset:7168
	buffer_load_dwordx4 v1, s[48:51], s10 offen lds
	s_mov_b32 m0, s39
	s_nop 0
	buffer_load_dwordx4 v1, s[48:51], s7 offen lds
	s_waitcnt lgkmcnt(8)
	s_barrier
	s_waitcnt lgkmcnt(0)
	s_setprio 1
	s_waitcnt lgkmcnt(7)
	v_mfma_f32_16x16x32_bf16 v[126:129], v[130:133], v[146:149], 0
	v_mfma_f32_16x16x32_bf16 v[122:125], v[138:141], v[146:149], 0
	s_waitcnt lgkmcnt(5)
	v_mfma_f32_16x16x32_bf16 v[110:113], v[130:133], v[154:157], 0
	v_mfma_f32_16x16x32_bf16 v[106:109], v[138:141], v[154:157], 0
	s_waitcnt lgkmcnt(3)
	v_mfma_f32_16x16x32_bf16 v[94:97], v[130:133], v[162:165], 0
	v_mfma_f32_16x16x32_bf16 v[90:93], v[138:141], v[162:165], 0
	s_waitcnt lgkmcnt(1)
	v_mfma_f32_16x16x32_bf16 v[78:81], v[130:133], v[170:173], 0
	v_mfma_f32_16x16x32_bf16 v[74:77], v[138:141], v[170:173], 0
	v_mfma_f32_16x16x32_bf16 v[126:129], v[134:137], v[150:153], v[126:129]
	v_mfma_f32_16x16x32_bf16 v[122:125], v[142:145], v[150:153], v[122:125]
	v_mfma_f32_16x16x32_bf16 v[110:113], v[134:137], v[158:161], v[110:113]
	v_mfma_f32_16x16x32_bf16 v[106:109], v[142:145], v[158:161], v[106:109]
	v_mfma_f32_16x16x32_bf16 v[94:97], v[134:137], v[166:169], v[94:97]
	v_mfma_f32_16x16x32_bf16 v[90:93], v[142:145], v[166:169], v[90:93]
	s_waitcnt lgkmcnt(0)
	v_mfma_f32_16x16x32_bf16 v[78:81], v[134:137], v[174:177], v[78:81]
	v_mfma_f32_16x16x32_bf16 v[74:77], v[142:145], v[174:177], v[74:77]
	s_setprio 0
	s_barrier
	s_mov_b32 m0, s16
	s_mov_b32 s10, s50
	s_mov_b32 s11, s51
	ds_read_b128 v[178:181], v197
	ds_read_b128 v[182:185], v197 offset:1024
	ds_read_b128 v[200:203], v197 offset:2048
	ds_read_b128 v[204:207], v197 offset:3072
	buffer_load_dwordx4 v192, s[8:11], s73 offen lds
	s_add_i32 s33, s73, 0x20000
	s_mov_b32 m0, s17
	s_nop 0
	buffer_load_dwordx4 v192, s[8:11], s33 offen lds
	s_barrier
	s_waitcnt lgkmcnt(0)
	s_setprio 1
	s_waitcnt lgkmcnt(3)
	v_mfma_f32_16x16x32_bf16 v[118:121], v[178:181], v[146:149], 0
	s_waitcnt lgkmcnt(1)
	v_mfma_f32_16x16x32_bf16 v[114:117], v[200:203], v[146:149], 0
	v_mfma_f32_16x16x32_bf16 v[102:105], v[178:181], v[154:157], 0
	v_mfma_f32_16x16x32_bf16 v[98:101], v[200:203], v[154:157], 0
	v_mfma_f32_16x16x32_bf16 v[86:89], v[178:181], v[162:165], 0
	v_mfma_f32_16x16x32_bf16 v[82:85], v[200:203], v[162:165], 0
	v_mfma_f32_16x16x32_bf16 v[70:73], v[178:181], v[170:173], 0
	v_mfma_f32_16x16x32_bf16 v[66:69], v[200:203], v[170:173], 0
	v_mfma_f32_16x16x32_bf16 v[118:121], v[182:185], v[150:153], v[118:121]
	s_waitcnt lgkmcnt(0)
	v_mfma_f32_16x16x32_bf16 v[114:117], v[204:207], v[150:153], v[114:117]
	v_mfma_f32_16x16x32_bf16 v[102:105], v[182:185], v[158:161], v[102:105]
	v_mfma_f32_16x16x32_bf16 v[98:101], v[204:207], v[158:161], v[98:101]
	v_mfma_f32_16x16x32_bf16 v[86:89], v[182:185], v[166:169], v[86:89]
	v_mfma_f32_16x16x32_bf16 v[82:85], v[204:207], v[166:169], v[82:85]
	v_mfma_f32_16x16x32_bf16 v[70:73], v[182:185], v[174:177], v[70:73]
	v_mfma_f32_16x16x32_bf16 v[66:69], v[204:207], v[174:177], v[66:69]
	s_setprio 0
	s_mov_b32 m0, s15
	s_barrier
	ds_read_b128 v[146:149], v196 offset:16384
	ds_read_b128 v[150:153], v196 offset:17408
	ds_read_b128 v[154:157], v196 offset:18432
	ds_read_b128 v[158:161], v196 offset:19456
	ds_read_b128 v[162:165], v196 offset:20480
	ds_read_b128 v[166:169], v196 offset:21504
	ds_read_b128 v[170:173], v196 offset:22528
	ds_read_b128 v[174:177], v196 offset:23552
	buffer_load_dwordx4 v1, s[48:51], s78 offen lds
	s_add_i32 s33, s78, 0x20000
	s_mov_b32 m0, s18
	s_nop 0
	buffer_load_dwordx4 v1, s[48:51], s33 offen lds
	s_barrier
	s_waitcnt lgkmcnt(0)
	s_setprio 1
	s_waitcnt lgkmcnt(7)
	v_mfma_f32_16x16x32_bf16 v[62:65], v[130:133], v[146:149], 0
	v_mfma_f32_16x16x32_bf16 v[58:61], v[138:141], v[146:149], 0
	s_waitcnt lgkmcnt(5)
	v_mfma_f32_16x16x32_bf16 v[46:49], v[130:133], v[154:157], 0
	v_mfma_f32_16x16x32_bf16 v[42:45], v[138:141], v[154:157], 0
	s_waitcnt lgkmcnt(3)
	v_mfma_f32_16x16x32_bf16 v[30:33], v[130:133], v[162:165], 0
	v_mfma_f32_16x16x32_bf16 v[26:29], v[138:141], v[162:165], 0
	s_waitcnt lgkmcnt(1)
	v_mfma_f32_16x16x32_bf16 v[14:17], v[130:133], v[170:173], 0
	v_mfma_f32_16x16x32_bf16 v[10:13], v[138:141], v[170:173], 0
	v_mfma_f32_16x16x32_bf16 v[62:65], v[134:137], v[150:153], v[62:65]
	v_mfma_f32_16x16x32_bf16 v[58:61], v[142:145], v[150:153], v[58:61]
	v_mfma_f32_16x16x32_bf16 v[46:49], v[134:137], v[158:161], v[46:49]
	v_mfma_f32_16x16x32_bf16 v[42:45], v[142:145], v[158:161], v[42:45]
	v_mfma_f32_16x16x32_bf16 v[30:33], v[134:137], v[166:169], v[30:33]
	v_mfma_f32_16x16x32_bf16 v[26:29], v[142:145], v[166:169], v[26:29]
	s_waitcnt lgkmcnt(0)
	v_mfma_f32_16x16x32_bf16 v[14:17], v[134:137], v[174:177], v[14:17]
	v_mfma_f32_16x16x32_bf16 v[10:13], v[142:145], v[174:177], v[10:13]
	s_setprio 0
	s_barrier
	s_mov_b32 m0, s19
	s_add_i32 s33, s73, 0x40000
	buffer_load_dwordx4 v192, s[8:11], s33 offen lds
	s_add_i32 s33, s73, 0x60000
	s_mov_b32 m0, s20
	s_nop 0
	buffer_load_dwordx4 v192, s[8:11], s33 offen lds
	s_cmp_eq_u32 s100, 0
	s_cbranch_scc1 .Lfw_10_a_p
	s_waitcnt vmcnt(24)
	s_mov_b32 s100, 0
	s_branch .Lfw_10_b_p

.LBB0_2826:
	s_lshl_b32 s58, s47, 19
	s_and_b64 s[6:7], s[6:7], exec
	v_mov_b32_e32 v2, 0
	s_cselect_b32 s6, s58, s13
	s_add_i32 s7, s13, 0x60080
	s_addk_i32 s12, 0x100
	s_mov_b32 s13, -2
	ds_read_b128 v[130:133], v196
	ds_read_b128 v[134:137], v196 offset:1024
	ds_read_b128 v[138:141], v196 offset:2048
	ds_read_b128 v[142:145], v196 offset:3072
	s_add_i32 s10, s7, 0xfffa0080
	s_cmp_eq_u32 s13, 12
	s_cselect_b32 s78, s6, s10
	s_cselect_b32 s73, s57, s12
	s_or_b32 s79, s78, 0x80
	s_add_i32 s10, s7, 0xfffe0000
	s_mov_b32 m0, s38
	ds_read_b128 v[146:149], v197
	ds_read_b128 v[150:153], v197 offset:1024
	ds_read_b128 v[154:157], v197 offset:2048
	ds_read_b128 v[158:161], v197 offset:3072
	ds_read_b128 v[162:165], v197 offset:4096
	ds_read_b128 v[166:169], v197 offset:5120
	ds_read_b128 v[170:173], v197 offset:6144
	ds_read_b128 v[174:177], v197 offset:7168
	buffer_load_dwordx4 v192, s[48:51], s10 offen lds
	s_mov_b32 m0, s39
	s_nop 0
	buffer_load_dwordx4 v192, s[48:51], s7 offen lds
	s_waitcnt lgkmcnt(8)
	s_barrier
	s_waitcnt lgkmcnt(0)
	s_setprio 1
	s_waitcnt lgkmcnt(7)
	v_mfma_f32_16x16x32_bf16 v[126:129], v[130:133], v[146:149], 0
	v_mfma_f32_16x16x32_bf16 v[122:125], v[138:141], v[146:149], 0
	s_waitcnt lgkmcnt(5)
	v_mfma_f32_16x16x32_bf16 v[110:113], v[130:133], v[154:157], 0
	v_mfma_f32_16x16x32_bf16 v[106:109], v[138:141], v[154:157], 0
	s_waitcnt lgkmcnt(3)
	v_mfma_f32_16x16x32_bf16 v[94:97], v[130:133], v[162:165], 0
	v_mfma_f32_16x16x32_bf16 v[90:93], v[138:141], v[162:165], 0
	s_waitcnt lgkmcnt(1)
	v_mfma_f32_16x16x32_bf16 v[78:81], v[130:133], v[170:173], 0
	v_mfma_f32_16x16x32_bf16 v[74:77], v[138:141], v[170:173], 0
	v_mfma_f32_16x16x32_bf16 v[126:129], v[134:137], v[150:153], v[126:129]
	v_mfma_f32_16x16x32_bf16 v[122:125], v[142:145], v[150:153], v[122:125]
	v_mfma_f32_16x16x32_bf16 v[110:113], v[134:137], v[158:161], v[110:113]
	v_mfma_f32_16x16x32_bf16 v[106:109], v[142:145], v[158:161], v[106:109]
	v_mfma_f32_16x16x32_bf16 v[94:97], v[134:137], v[166:169], v[94:97]
	v_mfma_f32_16x16x32_bf16 v[90:93], v[142:145], v[166:169], v[90:93]
	s_waitcnt lgkmcnt(0)
	v_mfma_f32_16x16x32_bf16 v[78:81], v[134:137], v[174:177], v[78:81]
	v_mfma_f32_16x16x32_bf16 v[74:77], v[142:145], v[174:177], v[74:77]
	s_setprio 0
	s_barrier
	s_mov_b32 m0, s16
	s_mov_b32 s10, s50
	s_mov_b32 s11, s51
	ds_read_b128 v[178:181], v198
	ds_read_b128 v[182:185], v198 offset:1024
	ds_read_b128 v[202:205], v198 offset:2048
	ds_read_b128 v[206:209], v198 offset:3072
	buffer_load_dwordx4 v193, s[8:11], s73 offen lds
	s_add_i32 s33, s73, 0x20000
	s_mov_b32 m0, s17
	s_nop 0
	buffer_load_dwordx4 v193, s[8:11], s33 offen lds
	s_barrier
	s_waitcnt lgkmcnt(0)
	s_setprio 1
	s_waitcnt lgkmcnt(3)
	v_mfma_f32_16x16x32_bf16 v[118:121], v[178:181], v[146:149], 0
	s_waitcnt lgkmcnt(1)
	v_mfma_f32_16x16x32_bf16 v[114:117], v[202:205], v[146:149], 0
	v_mfma_f32_16x16x32_bf16 v[102:105], v[178:181], v[154:157], 0
	v_mfma_f32_16x16x32_bf16 v[98:101], v[202:205], v[154:157], 0
	v_mfma_f32_16x16x32_bf16 v[86:89], v[178:181], v[162:165], 0
	v_mfma_f32_16x16x32_bf16 v[82:85], v[202:205], v[162:165], 0
	v_mfma_f32_16x16x32_bf16 v[70:73], v[178:181], v[170:173], 0
	v_mfma_f32_16x16x32_bf16 v[66:69], v[202:205], v[170:173], 0
	v_mfma_f32_16x16x32_bf16 v[118:121], v[182:185], v[150:153], v[118:121]
	s_waitcnt lgkmcnt(0)
	v_mfma_f32_16x16x32_bf16 v[114:117], v[206:209], v[150:153], v[114:117]
	v_mfma_f32_16x16x32_bf16 v[102:105], v[182:185], v[158:161], v[102:105]
	v_mfma_f32_16x16x32_bf16 v[98:101], v[206:209], v[158:161], v[98:101]
	v_mfma_f32_16x16x32_bf16 v[86:89], v[182:185], v[166:169], v[86:89]
	v_mfma_f32_16x16x32_bf16 v[82:85], v[206:209], v[166:169], v[82:85]
	v_mfma_f32_16x16x32_bf16 v[70:73], v[182:185], v[174:177], v[70:73]
	v_mfma_f32_16x16x32_bf16 v[66:69], v[206:209], v[174:177], v[66:69]
	s_setprio 0
	s_mov_b32 m0, s15
	s_barrier
	ds_read_b128 v[146:149], v197 offset:16384
	ds_read_b128 v[150:153], v197 offset:17408
	ds_read_b128 v[154:157], v197 offset:18432
	ds_read_b128 v[158:161], v197 offset:19456
	ds_read_b128 v[162:165], v197 offset:20480
	ds_read_b128 v[166:169], v197 offset:21504
	ds_read_b128 v[170:173], v197 offset:22528
	ds_read_b128 v[174:177], v197 offset:23552
	buffer_load_dwordx4 v192, s[48:51], s78 offen lds
	s_add_i32 s33, s78, 0x20000
	s_mov_b32 m0, s18
	s_nop 0
	buffer_load_dwordx4 v192, s[48:51], s33 offen lds
	s_barrier
	s_waitcnt lgkmcnt(0)
	s_setprio 1
	s_waitcnt lgkmcnt(7)
	v_mfma_f32_16x16x32_bf16 v[62:65], v[130:133], v[146:149], 0
	v_mfma_f32_16x16x32_bf16 v[58:61], v[138:141], v[146:149], 0
	s_waitcnt lgkmcnt(5)
	v_mfma_f32_16x16x32_bf16 v[46:49], v[130:133], v[154:157], 0
	v_mfma_f32_16x16x32_bf16 v[42:45], v[138:141], v[154:157], 0
	s_waitcnt lgkmcnt(3)
	v_mfma_f32_16x16x32_bf16 v[30:33], v[130:133], v[162:165], 0
	v_mfma_f32_16x16x32_bf16 v[26:29], v[138:141], v[162:165], 0
	s_waitcnt lgkmcnt(1)
	v_mfma_f32_16x16x32_bf16 v[14:17], v[130:133], v[170:173], 0
	v_mfma_f32_16x16x32_bf16 v[10:13], v[138:141], v[170:173], 0
	v_mfma_f32_16x16x32_bf16 v[62:65], v[134:137], v[150:153], v[62:65]
	v_mfma_f32_16x16x32_bf16 v[58:61], v[142:145], v[150:153], v[58:61]
	v_mfma_f32_16x16x32_bf16 v[46:49], v[134:137], v[158:161], v[46:49]
	v_mfma_f32_16x16x32_bf16 v[42:45], v[142:145], v[158:161], v[42:45]
	v_mfma_f32_16x16x32_bf16 v[30:33], v[134:137], v[166:169], v[30:33]
	v_mfma_f32_16x16x32_bf16 v[26:29], v[142:145], v[166:169], v[26:29]
	s_waitcnt lgkmcnt(0)
	v_mfma_f32_16x16x32_bf16 v[14:17], v[134:137], v[174:177], v[14:17]
	v_mfma_f32_16x16x32_bf16 v[10:13], v[142:145], v[174:177], v[10:13]
	s_setprio 0
	s_barrier
	s_mov_b32 m0, s19
	s_add_i32 s33, s73, 0x40000
	buffer_load_dwordx4 v193, s[8:11], s33 offen lds
	s_add_i32 s33, s73, 0x60000
	s_mov_b32 m0, s20
	s_nop 0
	buffer_load_dwordx4 v193, s[8:11], s33 offen lds
	s_cmp_eq_u32 s100, 0
	s_cbranch_scc1 .Lfw_14_a_p
	s_waitcnt vmcnt(24)
	s_mov_b32 s100, 0
	s_branch .Lfw_14_b_p
